# P2: the 128 workgroups with 9 units start ~7us late (they have an idle tail) so P2 epilogue store bursts of the two sets interleave
# baseline (speedup 1.0000x reference)
; __global__ void __launch_bounds__(NTHR, 2) fwd_megakernel(Args a) {
;     ...
;         pg8::Gemm g{H, WinT, M, INW, DM}; pg8::InOrder S; S.base.init(M, INW, G, blk);
;         pg8::EpiIn E{P, LOGF, lbl};
;         pg8::gemm_phase<pg8::EpiIn, pg8::InOrder, true, true>(lds, g, S, E);
.Lplace_ok:
	s_cmp_lt_u32 s55, 128
	s_cbranch_scc1 .Lp2skew_skip
	s_sleep 127
	s_sleep 127
